# attention PV(q-block 0): transposed V fragment reads double-buffered (P0 tuple reused as second buffer), 2 exposed LDS waits instead of 8
# baseline (speedup 1.0000x reference)
.LBB0_498:
	v_exp_f32_e32 v14, v128
	v_exp_f32_e32 v112, v112
	v_exp_f32_e32 v15, v129
	v_exp_f32_e32 v113, v113
	v_exp_f32_e32 v204, v130
	v_exp_f32_e32 v206, v114
	v_exp_f32_e32 v205, v131
	v_exp_f32_e32 v207, v115
	v_exp_f32_e32 v10, v132
	v_exp_f32_e32 v12, v116
	v_exp_f32_e32 v11, v133
	v_exp_f32_e32 v13, v117
	v_exp_f32_e32 v128, v134
	v_exp_f32_e32 v130, v118
	v_exp_f32_e32 v129, v135
	v_exp_f32_e32 v131, v119
	v_exp_f32_e32 v118, v136
	v_exp_f32_e32 v120, v120
	v_exp_f32_e32 v119, v137
	v_exp_f32_e32 v121, v121
	v_exp_f32_e32 v132, v138
	v_exp_f32_e32 v134, v122
	v_exp_f32_e32 v133, v139
	v_exp_f32_e32 v135, v123
	v_exp_f32_e32 v114, v140
	v_exp_f32_e32 v116, v124
	v_exp_f32_e32 v115, v141
	v_exp_f32_e32 v117, v125
	v_exp_f32_e32 v122, v142
	v_exp_f32_e32 v124, v126
	v_exp_f32_e32 v123, v143
	v_exp_f32_e32 v125, v127
	ds_read_b64_tr_b16 v[136:137], v219 offset:9216
	ds_read_b64_tr_b16 v[138:139], v219 offset:10752
	v_cvt_pk_bf16_f32 v140, v14, v15
	v_cvt_pk_bf16_f32 v141, v204, v205
	v_cvt_pk_bf16_f32 v142, v10, v11
	v_cvt_pk_bf16_f32 v143, v128, v129
	v_cvt_pk_bf16_f32 v230, v118, v119
	v_cvt_pk_bf16_f32 v231, v132, v133
	v_cvt_pk_bf16_f32 v232, v114, v115
	v_cvt_pk_bf16_f32 v233, v122, v123
	v_cvt_pk_bf16_f32 v244, v112, v113
	v_cvt_pk_bf16_f32 v245, v206, v207
	v_cvt_pk_bf16_f32 v246, v12, v13
	v_cvt_pk_bf16_f32 v247, v130, v131
	v_cvt_pk_bf16_f32 v248, v120, v121
	v_cvt_pk_bf16_f32 v249, v134, v135
	v_cvt_pk_bf16_f32 v250, v116, v117
	v_cvt_pk_bf16_f32 v251, v124, v125
	s_waitcnt lgkmcnt(0)
	v_mfma_f32_32x32x16_bf16 v[64:79], v[136:139], v[140:143], v[64:79]
	ds_read_b64_tr_b16 v[136:137], v219 offset:9280
	ds_read_b64_tr_b16 v[138:139], v219 offset:10816
	s_waitcnt lgkmcnt(0)
	v_mfma_f32_32x32x16_bf16 v[48:63], v[136:139], v[140:143], v[48:63]
	ds_read_b64_tr_b16 v[140:141], v219 offset:12288
	ds_read_b64_tr_b16 v[142:143], v219 offset:13824
	ds_read_b64_tr_b16 v[136:137], v219 offset:12352
	ds_read_b64_tr_b16 v[138:139], v219 offset:13888
	s_waitcnt lgkmcnt(2)
	v_mfma_f32_32x32x16_bf16 v[64:79], v[140:143], v[230:233], v[64:79]
	ds_read_b64_tr_b16 v[140:141], v219 offset:15360
	ds_read_b64_tr_b16 v[142:143], v219 offset:16896
	s_waitcnt lgkmcnt(2)
	v_mfma_f32_32x32x16_bf16 v[48:63], v[136:139], v[230:233], v[48:63]
	ds_read_b64_tr_b16 v[136:137], v219 offset:15424
	ds_read_b64_tr_b16 v[138:139], v219 offset:16960
	s_waitcnt lgkmcnt(2)
	v_mfma_f32_32x32x16_bf16 v[64:79], v[140:143], v[244:247], v[64:79]
	ds_read_b64_tr_b16 v[140:141], v219 offset:18432
	ds_read_b64_tr_b16 v[142:143], v219 offset:19968
	s_waitcnt lgkmcnt(2)
	v_mfma_f32_32x32x16_bf16 v[48:63], v[136:139], v[244:247], v[48:63]
	ds_read_b64_tr_b16 v[136:137], v219 offset:18496
	ds_read_b64_tr_b16 v[138:139], v219 offset:20032
	s_waitcnt lgkmcnt(2)
	v_mfma_f32_32x32x16_bf16 v[64:79], v[140:143], v[248:251], v[64:79]
	s_waitcnt lgkmcnt(0)
	v_mfma_f32_32x32x16_bf16 v[48:63], v[136:139], v[248:251], v[48:63]
	s_and_b64 vcc, exec, s[4:5]
	s_cbranch_vccnz .LBB0_500
	v_add_u32_e32 v127, v212, v240
	v_add_u32_e32 v138, 0xffffff7f, v127
	v_cmp_lt_u32_e32 vcc, s91, v138
	v_add_u32_e32 v139, 0xffffff5f, v127
	v_cmp_lt_u32_e64 s[20:21], s91, v139
	v_add_u32_e32 v140, 0xffffff7e, v127
	v_cmp_lt_u32_e64 s[40:41], s91, v140
	v_cndmask_b32_e32 v96, v234, v96, vcc
	v_add_u32_e32 v138, 0xffffff5e, v127
	v_cmp_lt_u32_e32 vcc, s91, v138
	v_cndmask_b32_e64 v80, v234, v80, s[20:21]
	v_add_u32_e32 v139, 0xffffff7d, v127
	v_cmp_lt_u32_e64 s[20:21], s91, v139
	v_cndmask_b32_e64 v97, v234, v97, s[40:41]
	v_add_u32_e32 v140, 0xffffff5d, v127
	v_cmp_lt_u32_e64 s[40:41], s91, v140
	v_cndmask_b32_e32 v81, v234, v81, vcc
	v_add_u32_e32 v138, 0xffffff7c, v127
	v_cmp_lt_u32_e32 vcc, s91, v138
	v_cndmask_b32_e64 v98, v234, v98, s[20:21]
	v_add_u32_e32 v139, 0xffffff5c, v127
	v_cmp_lt_u32_e64 s[20:21], s91, v139
	v_cndmask_b32_e64 v82, v234, v82, s[40:41]
	v_add_u32_e32 v140, 0xffffff77, v127
	v_cmp_lt_u32_e64 s[40:41], s91, v140
	v_cndmask_b32_e32 v99, v234, v99, vcc
	v_add_u32_e32 v138, 0xffffff57, v127
	v_cmp_lt_u32_e32 vcc, s91, v138
	v_cndmask_b32_e64 v83, v234, v83, s[20:21]
	v_add_u32_e32 v139, 0xffffff76, v127
	v_cmp_lt_u32_e64 s[20:21], s91, v139
	v_cndmask_b32_e64 v100, v234, v100, s[40:41]
	v_add_u32_e32 v140, 0xffffff56, v127
	v_cmp_lt_u32_e64 s[40:41], s91, v140
	v_cndmask_b32_e32 v84, v234, v84, vcc
	v_add_u32_e32 v138, 0xffffff75, v127
	v_cmp_lt_u32_e32 vcc, s91, v138
	v_cndmask_b32_e64 v101, v234, v101, s[20:21]
	v_add_u32_e32 v139, 0xffffff55, v127
	v_cmp_lt_u32_e64 s[20:21], s91, v139
	v_cndmask_b32_e64 v85, v234, v85, s[40:41]
	v_add_u32_e32 v140, 0xffffff74, v127
	v_cmp_lt_u32_e64 s[40:41], s91, v140
	v_cndmask_b32_e32 v102, v234, v102, vcc
	v_add_u32_e32 v138, 0xffffff54, v127
	v_cmp_lt_u32_e32 vcc, s91, v138
	v_cndmask_b32_e64 v86, v234, v86, s[20:21]
	v_add_u32_e32 v139, 0xffffff6f, v127
	v_cmp_lt_u32_e64 s[20:21], s91, v139
	v_cndmask_b32_e64 v103, v234, v103, s[40:41]
	v_add_u32_e32 v140, 0xffffff4f, v127
	v_cmp_lt_u32_e64 s[40:41], s91, v140
	v_cndmask_b32_e32 v87, v234, v87, vcc
	v_add_u32_e32 v138, 0xffffff6e, v127
	v_cmp_lt_u32_e32 vcc, s91, v138
	v_cndmask_b32_e64 v104, v234, v104, s[20:21]
	v_add_u32_e32 v139, 0xffffff4e, v127
	v_cmp_lt_u32_e64 s[20:21], s91, v139
	v_cndmask_b32_e64 v88, v234, v88, s[40:41]
	v_add_u32_e32 v140, 0xffffff6d, v127
	v_cmp_lt_u32_e64 s[40:41], s91, v140
	v_cndmask_b32_e32 v105, v234, v105, vcc
	v_add_u32_e32 v138, 0xffffff4d, v127
	v_cmp_lt_u32_e32 vcc, s91, v138
	v_cndmask_b32_e64 v89, v234, v89, s[20:21]
	v_add_u32_e32 v139, 0xffffff6c, v127
	v_cmp_lt_u32_e64 s[20:21], s91, v139
	v_cndmask_b32_e64 v106, v234, v106, s[40:41]
	v_add_u32_e32 v140, 0xffffff4c, v127
	v_cmp_lt_u32_e64 s[40:41], s91, v140
	v_cndmask_b32_e32 v90, v234, v90, vcc
	v_add_u32_e32 v138, 0xffffff67, v127
	v_cmp_lt_u32_e32 vcc, s91, v138
	v_cndmask_b32_e64 v107, v234, v107, s[20:21]
	v_add_u32_e32 v139, 0xffffff47, v127
	v_cmp_lt_u32_e64 s[20:21], s91, v139
	v_cndmask_b32_e64 v91, v234, v91, s[40:41]
	v_add_u32_e32 v140, 0xffffff66, v127
	v_cmp_lt_u32_e64 s[40:41], s91, v140
	v_cndmask_b32_e32 v108, v234, v108, vcc
	v_add_u32_e32 v138, 0xffffff46, v127
	v_cmp_lt_u32_e32 vcc, s91, v138
	v_cndmask_b32_e64 v92, v234, v92, s[20:21]
	v_add_u32_e32 v139, 0xffffff65, v127
	v_cmp_lt_u32_e64 s[20:21], s91, v139
	v_cndmask_b32_e64 v109, v234, v109, s[40:41]
	v_add_u32_e32 v140, 0xffffff45, v127
	v_cmp_lt_u32_e64 s[40:41], s91, v140
	v_cndmask_b32_e32 v93, v234, v93, vcc
	v_add_u32_e32 v138, 0xffffff64, v127
	v_cmp_lt_u32_e32 vcc, s91, v138
	v_cndmask_b32_e64 v110, v234, v110, s[20:21]
	v_add_u32_e32 v139, 0xffffff44, v127
	v_cmp_lt_u32_e64 s[20:21], s91, v139
	v_cndmask_b32_e64 v94, v234, v94, s[40:41]
	s_nop 0
	v_cndmask_b32_e32 v111, v234, v111, vcc
	v_cndmask_b32_e64 v95, v234, v95, s[20:21]
